# P3 bisection: removed the 24 compiler-inserted s_nop 0 between the inline-asm compare/count groups (no hazard between groups)
# baseline (speedup 1.0000x reference)
.LBB0_720:
	s_lshl_b32 s21, 1, s2
	s_or_b32 s22, s21, s1
	s_andn2_b64 vcc, exec, s[8:9]
	s_or_b32 s21, s21, s0
	s_cbranch_vccnz .LBB0_731
	v_cmp_le_u32_e64 s[24:25], s22, v245
	v_cmp_le_u32_e64 s[26:27], s22, v244
	v_cmp_le_u32_e64 s[28:29], s22, v243
	v_cmp_le_u32_e64 s[30:31], s22, v242
	v_cndmask_b32_e64 v251, 0, 1, s[24:25]
	v_cndmask_b32_e64 v250, 0, 1, s[26:27]
	v_cndmask_b32_e64 v253, 0, 1, s[28:29]
	v_cndmask_b32_e64 v252, 0, 1, s[30:31]
	v_cmp_le_u32_e64 s[24:25], s21, v215
	v_cmp_le_u32_e64 s[26:27], s21, v108
	v_cmp_le_u32_e64 s[28:29], s21, v107
	v_cmp_le_u32_e64 s[30:31], s21, v106
	v_cndmask_b32_e64 v247, 0, 1, s[24:25]
	v_cndmask_b32_e64 v246, 0, 1, s[26:27]
	v_cndmask_b32_e64 v248, 0, 1, s[28:29]
	v_cndmask_b32_e64 v249, 0, 1, s[30:31]
	v_cmp_le_u32_e64 s[24:25], s22, v241
	v_cmp_le_u32_e64 s[26:27], s22, v240
	v_cmp_le_u32_e64 s[28:29], s22, v239
	v_cmp_le_u32_e64 s[30:31], s22, v238
	v_addc_co_u32_e64 v251, s[24:25], v251, 0, s[24:25]
	v_addc_co_u32_e64 v250, s[26:27], v250, 0, s[26:27]
	v_addc_co_u32_e64 v253, s[28:29], v253, 0, s[28:29]
	v_addc_co_u32_e64 v252, s[30:31], v252, 0, s[30:31]
	v_cmp_le_u32_e64 s[24:25], s21, v105
	v_cmp_le_u32_e64 s[26:27], s21, v104
	v_cmp_le_u32_e64 s[28:29], s21, v103
	v_cmp_le_u32_e64 s[30:31], s21, v102
	v_addc_co_u32_e64 v247, s[24:25], v247, 0, s[24:25]
	v_addc_co_u32_e64 v246, s[26:27], v246, 0, s[26:27]
	v_addc_co_u32_e64 v248, s[28:29], v248, 0, s[28:29]
	v_addc_co_u32_e64 v249, s[30:31], v249, 0, s[30:31]
	s_andn2_b64 vcc, exec, s[10:11]
	s_cbranch_vccnz .LBB0_723
.LBB0_722:
	v_cmp_le_u32_e64 s[24:25], s22, v237
	v_cmp_le_u32_e64 s[26:27], s22, v236
	v_cmp_le_u32_e64 s[28:29], s22, v235
	v_cmp_le_u32_e64 s[30:31], s22, v234
	v_addc_co_u32_e64 v251, s[24:25], v251, 0, s[24:25]
	v_addc_co_u32_e64 v250, s[26:27], v250, 0, s[26:27]
	v_addc_co_u32_e64 v253, s[28:29], v253, 0, s[28:29]
	v_addc_co_u32_e64 v252, s[30:31], v252, 0, s[30:31]
	v_cmp_le_u32_e64 s[24:25], s21, v101
	v_cmp_le_u32_e64 s[26:27], s21, v100
	v_cmp_le_u32_e64 s[28:29], s21, v99
	v_cmp_le_u32_e64 s[30:31], s21, v98
	v_addc_co_u32_e64 v247, s[24:25], v247, 0, s[24:25]
	v_addc_co_u32_e64 v246, s[26:27], v246, 0, s[26:27]
	v_addc_co_u32_e64 v248, s[28:29], v248, 0, s[28:29]
	v_addc_co_u32_e64 v249, s[30:31], v249, 0, s[30:31]
	v_cmp_le_u32_e64 s[24:25], s22, v233
	v_cmp_le_u32_e64 s[26:27], s22, v232
	v_cmp_le_u32_e64 s[28:29], s22, v231
	v_cmp_le_u32_e64 s[30:31], s22, v230
	v_addc_co_u32_e64 v251, s[24:25], v251, 0, s[24:25]
	v_addc_co_u32_e64 v250, s[26:27], v250, 0, s[26:27]
	v_addc_co_u32_e64 v253, s[28:29], v253, 0, s[28:29]
	v_addc_co_u32_e64 v252, s[30:31], v252, 0, s[30:31]
	v_cmp_le_u32_e64 s[24:25], s21, v97
	v_cmp_le_u32_e64 s[26:27], s21, v96
	v_cmp_le_u32_e64 s[28:29], s21, v95
	v_cmp_le_u32_e64 s[30:31], s21, v94
	v_addc_co_u32_e64 v247, s[24:25], v247, 0, s[24:25]
	v_addc_co_u32_e64 v246, s[26:27], v246, 0, s[26:27]
	v_addc_co_u32_e64 v248, s[28:29], v248, 0, s[28:29]
	v_addc_co_u32_e64 v249, s[30:31], v249, 0, s[30:31]
.LBB0_723:
	s_andn2_b64 vcc, exec, s[12:13]
	s_cbranch_vccnz .LBB0_725
	v_cmp_le_u32_e64 s[24:25], s22, v229
	v_cmp_le_u32_e64 s[26:27], s22, v228
	v_cmp_le_u32_e64 s[28:29], s22, v227
	v_cmp_le_u32_e64 s[30:31], s22, v226
	v_addc_co_u32_e64 v251, s[24:25], v251, 0, s[24:25]
	v_addc_co_u32_e64 v250, s[26:27], v250, 0, s[26:27]
	v_addc_co_u32_e64 v253, s[28:29], v253, 0, s[28:29]
	v_addc_co_u32_e64 v252, s[30:31], v252, 0, s[30:31]
	v_cmp_le_u32_e64 s[24:25], s21, v93
	v_cmp_le_u32_e64 s[26:27], s21, v92
	v_cmp_le_u32_e64 s[28:29], s21, v91
	v_cmp_le_u32_e64 s[30:31], s21, v90
	v_addc_co_u32_e64 v247, s[24:25], v247, 0, s[24:25]
	v_addc_co_u32_e64 v246, s[26:27], v246, 0, s[26:27]
	v_addc_co_u32_e64 v248, s[28:29], v248, 0, s[28:29]
	v_addc_co_u32_e64 v249, s[30:31], v249, 0, s[30:31]
	v_cmp_le_u32_e64 s[24:25], s22, v225
	v_cmp_le_u32_e64 s[26:27], s22, v224
	v_cmp_le_u32_e64 s[28:29], s22, v223
	v_cmp_le_u32_e64 s[30:31], s22, v222
	v_addc_co_u32_e64 v251, s[24:25], v251, 0, s[24:25]
	v_addc_co_u32_e64 v250, s[26:27], v250, 0, s[26:27]
	v_addc_co_u32_e64 v253, s[28:29], v253, 0, s[28:29]
	v_addc_co_u32_e64 v252, s[30:31], v252, 0, s[30:31]
	v_cmp_le_u32_e64 s[24:25], s21, v89
	v_cmp_le_u32_e64 s[26:27], s21, v88
	v_cmp_le_u32_e64 s[28:29], s21, v87
	v_cmp_le_u32_e64 s[30:31], s21, v86
	v_addc_co_u32_e64 v247, s[24:25], v247, 0, s[24:25]
	v_addc_co_u32_e64 v246, s[26:27], v246, 0, s[26:27]
	v_addc_co_u32_e64 v248, s[28:29], v248, 0, s[28:29]
	v_addc_co_u32_e64 v249, s[30:31], v249, 0, s[30:31]
	s_andn2_b64 vcc, exec, s[14:15]
	s_cbranch_vccz .LBB0_726
	s_branch .LBB0_727

.LBB0_726:
	v_cmp_le_u32_e64 s[24:25], s22, v221
	v_cmp_le_u32_e64 s[26:27], s22, v220
	v_cmp_le_u32_e64 s[28:29], s22, v219
	v_cmp_le_u32_e64 s[30:31], s22, v218
	v_addc_co_u32_e64 v251, s[24:25], v251, 0, s[24:25]
	v_addc_co_u32_e64 v250, s[26:27], v250, 0, s[26:27]
	v_addc_co_u32_e64 v253, s[28:29], v253, 0, s[28:29]
	v_addc_co_u32_e64 v252, s[30:31], v252, 0, s[30:31]
	v_cmp_le_u32_e64 s[24:25], s21, v85
	v_cmp_le_u32_e64 s[26:27], s21, v84
	v_cmp_le_u32_e64 s[28:29], s21, v83
	v_cmp_le_u32_e64 s[30:31], s21, v82
	v_addc_co_u32_e64 v247, s[24:25], v247, 0, s[24:25]
	v_addc_co_u32_e64 v246, s[26:27], v246, 0, s[26:27]
	v_addc_co_u32_e64 v248, s[28:29], v248, 0, s[28:29]
	v_addc_co_u32_e64 v249, s[30:31], v249, 0, s[30:31]
	v_cmp_le_u32_e64 s[24:25], s22, v217
	v_cmp_le_u32_e64 s[26:27], s22, v216
	v_cmp_le_u32_e64 s[28:29], s22, v77
	v_cmp_le_u32_e64 s[30:31], s22, v76
	v_addc_co_u32_e64 v251, s[24:25], v251, 0, s[24:25]
	v_addc_co_u32_e64 v250, s[26:27], v250, 0, s[26:27]
	v_addc_co_u32_e64 v253, s[28:29], v253, 0, s[28:29]
	v_addc_co_u32_e64 v252, s[30:31], v252, 0, s[30:31]
	v_cmp_le_u32_e64 s[24:25], s21, v81
	v_cmp_le_u32_e64 s[26:27], s21, v80
	v_cmp_le_u32_e64 s[28:29], s21, v79
	v_cmp_le_u32_e64 s[30:31], s21, v78
	v_addc_co_u32_e64 v247, s[24:25], v247, 0, s[24:25]
	v_addc_co_u32_e64 v246, s[26:27], v246, 0, s[26:27]
	v_addc_co_u32_e64 v248, s[28:29], v248, 0, s[28:29]
	v_addc_co_u32_e64 v249, s[30:31], v249, 0, s[30:31]

.LBB0_1727:
	s_lshl_b32 s19, 1, s2
	s_or_b32 s20, s19, s1
	s_andn2_b64 vcc, exec, s[4:5]
	s_or_b32 s19, s19, s0
	s_cbranch_vccnz .LBB0_1738
	v_cmp_le_u32_e64 s[22:23], s20, v241
	v_cmp_le_u32_e64 s[24:25], s20, v240
	v_cmp_le_u32_e64 s[26:27], s20, v239
	v_cmp_le_u32_e64 s[28:29], s20, v238
	v_cndmask_b32_e64 v247, 0, 1, s[22:23]
	v_cndmask_b32_e64 v246, 0, 1, s[24:25]
	v_cndmask_b32_e64 v249, 0, 1, s[26:27]
	v_cndmask_b32_e64 v248, 0, 1, s[28:29]
	v_cmp_le_u32_e64 s[22:23], s19, v211
	v_cmp_le_u32_e64 s[24:25], s19, v108
	v_cmp_le_u32_e64 s[26:27], s19, v107
	v_cmp_le_u32_e64 s[28:29], s19, v106
	v_cndmask_b32_e64 v243, 0, 1, s[22:23]
	v_cndmask_b32_e64 v242, 0, 1, s[24:25]
	v_cndmask_b32_e64 v244, 0, 1, s[26:27]
	v_cndmask_b32_e64 v245, 0, 1, s[28:29]
	v_cmp_le_u32_e64 s[22:23], s20, v237
	v_cmp_le_u32_e64 s[24:25], s20, v236
	v_cmp_le_u32_e64 s[26:27], s20, v235
	v_cmp_le_u32_e64 s[28:29], s20, v234
	v_addc_co_u32_e64 v247, s[22:23], v247, 0, s[22:23]
	v_addc_co_u32_e64 v246, s[24:25], v246, 0, s[24:25]
	v_addc_co_u32_e64 v249, s[26:27], v249, 0, s[26:27]
	v_addc_co_u32_e64 v248, s[28:29], v248, 0, s[28:29]
	v_cmp_le_u32_e64 s[22:23], s19, v105
	v_cmp_le_u32_e64 s[24:25], s19, v104
	v_cmp_le_u32_e64 s[26:27], s19, v103
	v_cmp_le_u32_e64 s[28:29], s19, v102
	v_addc_co_u32_e64 v243, s[22:23], v243, 0, s[22:23]
	v_addc_co_u32_e64 v242, s[24:25], v242, 0, s[24:25]
	v_addc_co_u32_e64 v244, s[26:27], v244, 0, s[26:27]
	v_addc_co_u32_e64 v245, s[28:29], v245, 0, s[28:29]
	s_andn2_b64 vcc, exec, s[8:9]
	s_cbranch_vccnz .LBB0_1730
.LBB0_1729:
	v_cmp_le_u32_e64 s[22:23], s20, v233
	v_cmp_le_u32_e64 s[24:25], s20, v232
	v_cmp_le_u32_e64 s[26:27], s20, v231
	v_cmp_le_u32_e64 s[28:29], s20, v230
	v_addc_co_u32_e64 v247, s[22:23], v247, 0, s[22:23]
	v_addc_co_u32_e64 v246, s[24:25], v246, 0, s[24:25]
	v_addc_co_u32_e64 v249, s[26:27], v249, 0, s[26:27]
	v_addc_co_u32_e64 v248, s[28:29], v248, 0, s[28:29]
	v_cmp_le_u32_e64 s[22:23], s19, v101
	v_cmp_le_u32_e64 s[24:25], s19, v100
	v_cmp_le_u32_e64 s[26:27], s19, v99
	v_cmp_le_u32_e64 s[28:29], s19, v98
	v_addc_co_u32_e64 v243, s[22:23], v243, 0, s[22:23]
	v_addc_co_u32_e64 v242, s[24:25], v242, 0, s[24:25]
	v_addc_co_u32_e64 v244, s[26:27], v244, 0, s[26:27]
	v_addc_co_u32_e64 v245, s[28:29], v245, 0, s[28:29]
	v_cmp_le_u32_e64 s[22:23], s20, v229
	v_cmp_le_u32_e64 s[24:25], s20, v228
	v_cmp_le_u32_e64 s[26:27], s20, v227
	v_cmp_le_u32_e64 s[28:29], s20, v226
	v_addc_co_u32_e64 v247, s[22:23], v247, 0, s[22:23]
	v_addc_co_u32_e64 v246, s[24:25], v246, 0, s[24:25]
	v_addc_co_u32_e64 v249, s[26:27], v249, 0, s[26:27]
	v_addc_co_u32_e64 v248, s[28:29], v248, 0, s[28:29]
	v_cmp_le_u32_e64 s[22:23], s19, v97
	v_cmp_le_u32_e64 s[24:25], s19, v96
	v_cmp_le_u32_e64 s[26:27], s19, v95
	v_cmp_le_u32_e64 s[28:29], s19, v94
	v_addc_co_u32_e64 v243, s[22:23], v243, 0, s[22:23]
	v_addc_co_u32_e64 v242, s[24:25], v242, 0, s[24:25]
	v_addc_co_u32_e64 v244, s[26:27], v244, 0, s[26:27]
	v_addc_co_u32_e64 v245, s[28:29], v245, 0, s[28:29]
.LBB0_1730:
	s_andn2_b64 vcc, exec, s[10:11]
	s_cbranch_vccnz .LBB0_1732
	v_cmp_le_u32_e64 s[22:23], s20, v225
	v_cmp_le_u32_e64 s[24:25], s20, v224
	v_cmp_le_u32_e64 s[26:27], s20, v223
	v_cmp_le_u32_e64 s[28:29], s20, v222
	v_addc_co_u32_e64 v247, s[22:23], v247, 0, s[22:23]
	v_addc_co_u32_e64 v246, s[24:25], v246, 0, s[24:25]
	v_addc_co_u32_e64 v249, s[26:27], v249, 0, s[26:27]
	v_addc_co_u32_e64 v248, s[28:29], v248, 0, s[28:29]
	v_cmp_le_u32_e64 s[22:23], s19, v93
	v_cmp_le_u32_e64 s[24:25], s19, v92
	v_cmp_le_u32_e64 s[26:27], s19, v91
	v_cmp_le_u32_e64 s[28:29], s19, v90
	v_addc_co_u32_e64 v243, s[22:23], v243, 0, s[22:23]
	v_addc_co_u32_e64 v242, s[24:25], v242, 0, s[24:25]
	v_addc_co_u32_e64 v244, s[26:27], v244, 0, s[26:27]
	v_addc_co_u32_e64 v245, s[28:29], v245, 0, s[28:29]
	v_cmp_le_u32_e64 s[22:23], s20, v221
	v_cmp_le_u32_e64 s[24:25], s20, v220
	v_cmp_le_u32_e64 s[26:27], s20, v219
	v_cmp_le_u32_e64 s[28:29], s20, v218
	v_addc_co_u32_e64 v247, s[22:23], v247, 0, s[22:23]
	v_addc_co_u32_e64 v246, s[24:25], v246, 0, s[24:25]
	v_addc_co_u32_e64 v249, s[26:27], v249, 0, s[26:27]
	v_addc_co_u32_e64 v248, s[28:29], v248, 0, s[28:29]
	v_cmp_le_u32_e64 s[22:23], s19, v89
	v_cmp_le_u32_e64 s[24:25], s19, v88
	v_cmp_le_u32_e64 s[26:27], s19, v87
	v_cmp_le_u32_e64 s[28:29], s19, v86
	v_addc_co_u32_e64 v243, s[22:23], v243, 0, s[22:23]
	v_addc_co_u32_e64 v242, s[24:25], v242, 0, s[24:25]
	v_addc_co_u32_e64 v244, s[26:27], v244, 0, s[26:27]
	v_addc_co_u32_e64 v245, s[28:29], v245, 0, s[28:29]
	s_andn2_b64 vcc, exec, s[12:13]
	s_cbranch_vccz .LBB0_1733
	s_branch .LBB0_1734

.LBB0_1733:
	v_cmp_le_u32_e64 s[22:23], s20, v217
	v_cmp_le_u32_e64 s[24:25], s20, v216
	v_cmp_le_u32_e64 s[26:27], s20, v215
	v_cmp_le_u32_e64 s[28:29], s20, v214
	v_addc_co_u32_e64 v247, s[22:23], v247, 0, s[22:23]
	v_addc_co_u32_e64 v246, s[24:25], v246, 0, s[24:25]
	v_addc_co_u32_e64 v249, s[26:27], v249, 0, s[26:27]
	v_addc_co_u32_e64 v248, s[28:29], v248, 0, s[28:29]
	v_cmp_le_u32_e64 s[22:23], s19, v85
	v_cmp_le_u32_e64 s[24:25], s19, v84
	v_cmp_le_u32_e64 s[26:27], s19, v83
	v_cmp_le_u32_e64 s[28:29], s19, v82
	v_addc_co_u32_e64 v243, s[22:23], v243, 0, s[22:23]
	v_addc_co_u32_e64 v242, s[24:25], v242, 0, s[24:25]
	v_addc_co_u32_e64 v244, s[26:27], v244, 0, s[26:27]
	v_addc_co_u32_e64 v245, s[28:29], v245, 0, s[28:29]
	v_cmp_le_u32_e64 s[22:23], s20, v213
	v_cmp_le_u32_e64 s[24:25], s20, v212
	v_cmp_le_u32_e64 s[26:27], s20, v77
	v_cmp_le_u32_e64 s[28:29], s20, v76
	v_addc_co_u32_e64 v247, s[22:23], v247, 0, s[22:23]
	v_addc_co_u32_e64 v246, s[24:25], v246, 0, s[24:25]
	v_addc_co_u32_e64 v249, s[26:27], v249, 0, s[26:27]
	v_addc_co_u32_e64 v248, s[28:29], v248, 0, s[28:29]
	v_cmp_le_u32_e64 s[22:23], s19, v81
	v_cmp_le_u32_e64 s[24:25], s19, v80
	v_cmp_le_u32_e64 s[26:27], s19, v79
	v_cmp_le_u32_e64 s[28:29], s19, v78
	v_addc_co_u32_e64 v243, s[22:23], v243, 0, s[22:23]
	v_addc_co_u32_e64 v242, s[24:25], v242, 0, s[24:25]
	v_addc_co_u32_e64 v244, s[26:27], v244, 0, s[26:27]
	v_addc_co_u32_e64 v245, s[28:29], v245, 0, s[28:29]
